# attention: deeper LDS fragment prefetch (6 K sets, 8 V sets in free S/P regs), QK pre-reads hoisted above PV, permlane32_swap row max, scalar instead of packed f32 softmax ops
# speedup vs baseline: 1.0081x; 1.0058x over previous
.Lat_nosq1:
	s_mov_b32 s36, 0
	s_mov_b32 s37, 0
	s_mov_b32 s39, 0
.Lat_w0_2:
	s_waitcnt vmcnt(0)
.Lat_w1_2:
	v_add_u32_e32 v0, s36, v225
	ds_write_b128 v0, v[198:201]
	ds_write_b128 v0, v[202:205] offset:12800
	v_add_u32_e32 v0, s36, v226
	ds_write_b128 v0, v[206:209]
	v_add_u32_e32 v0, s37, v227
	ds_write2_b64 v0, v[210:211], v[212:213] offset1:1
	v_add_u32_e32 v0, s37, v228
	ds_write2_b64 v0, v[214:215], v[216:217] offset1:1
	s_cmp_lg_u32 s34, 0
	s_cbranch_scc1 .Lat_nosc2
	v_add_f32_e32 v247, v218, v219
	v_mov_b32_e32 v242, 0x358637bd
	v_fmamk_f32 v247, v247, 0x3baaaaab, v242
	v_rsq_f32_e32 v247, v247
	v_add_u32_e32 v0, s39, v229
	s_nop 0
	ds_write_b32 v0, v247

.Lat_loop:
	s_add_i32 s65, s22, 1
	s_cmp_ge_u32 s65, s23
	s_cbranch_scc1 .Lat_x_nostore
	s_add_i32 s72, s24, 1
	s_cmp_eq_u32 s72, 3
	s_cselect_b32 s72, 0, s72
	s_mul_i32 s36, s72, 0x6400
	s_mul_i32 s37, s72, 0x4400
	s_lshl_b32 s39, s72, 8
.Lat_w0_4:
	s_waitcnt vmcnt(0)

.Lat_nosq5:
.Lat_x_nostore:
	s_cmp_gt_i32 s22, s25
	s_cbranch_scc1 .Lat_x_nopre
	s_mul_i32 s36, s24, 0x6400
	v_add_u32_e32 v0, s36, v230
	ds_read_b128 v[162:165], v0
	ds_read_b128 v[166:169], v0 offset:12800
	ds_read_b128 v[170:173], v0 offset:32
	ds_read_b128 v[174:177], v0 offset:12832
	ds_read_b128 v[178:181], v0 offset:64
	ds_read_b128 v[182:185], v0 offset:12864
	ds_read_b128 v[186:189], v0 offset:96
	ds_read_b128 v[190:193], v0 offset:12896

.Lat_x_pvb:
	s_mul_i32 s37, s72, 0x4400
	v_add_u32_e32 v243, s37, v231
	v_add_u32_e32 v244, 0x1100, v243
	v_add_u32_e32 v245, 0x2200, v243
	v_add_u32_e32 v246, 0x3300, v243
	ds_read2_b64 v[66:69], v243 offset0:0 offset1:2
	ds_read2_b64 v[70:73], v244 offset0:0 offset1:2
	ds_read2_b64 v[74:77], v245 offset0:0 offset1:2
	ds_read2_b64 v[78:81], v246 offset0:0 offset1:2
	ds_read2_b64 v[82:85], v243 offset0:4 offset1:6
	ds_read2_b64 v[86:89], v244 offset0:4 offset1:6
	ds_read2_b64 v[90:93], v245 offset0:4 offset1:6
	s_waitcnt lgkmcnt(6)
	v_mfma_f32_32x32x16_bf16 v[2:17], v[66:69], v[146:149], v[2:17]
	ds_read2_b64 v[94:97], v246 offset0:4 offset1:6
	s_waitcnt lgkmcnt(6)
	v_mfma_f32_32x32x16_bf16 v[18:33], v[70:73], v[146:149], v[18:33]
	ds_read2_b64 v[66:69], v243 offset0:8 offset1:10
	s_waitcnt lgkmcnt(6)
	v_mfma_f32_32x32x16_bf16 v[34:49], v[74:77], v[146:149], v[34:49]
	ds_read2_b64 v[70:73], v244 offset0:8 offset1:10
	s_waitcnt lgkmcnt(6)
	v_mfma_f32_32x32x16_bf16 v[50:65], v[78:81], v[146:149], v[50:65]
	ds_read2_b64 v[74:77], v245 offset0:8 offset1:10
	s_waitcnt lgkmcnt(6)
	v_mfma_f32_32x32x16_bf16 v[2:17], v[82:85], v[150:153], v[2:17]
	ds_read2_b64 v[78:81], v246 offset0:8 offset1:10
	s_waitcnt lgkmcnt(6)
	v_mfma_f32_32x32x16_bf16 v[18:33], v[86:89], v[150:153], v[18:33]
	ds_read2_b64 v[82:85], v243 offset0:12 offset1:14
	s_waitcnt lgkmcnt(6)
	v_mfma_f32_32x32x16_bf16 v[34:49], v[90:93], v[150:153], v[34:49]
	ds_read2_b64 v[86:89], v244 offset0:12 offset1:14
	s_waitcnt lgkmcnt(6)
	v_mfma_f32_32x32x16_bf16 v[50:65], v[94:97], v[150:153], v[50:65]
	ds_read2_b64 v[90:93], v245 offset0:12 offset1:14
	s_waitcnt lgkmcnt(6)
	v_mfma_f32_32x32x16_bf16 v[2:17], v[66:69], v[154:157], v[2:17]
	ds_read2_b64 v[94:97], v246 offset0:12 offset1:14
	s_waitcnt lgkmcnt(6)
	v_mfma_f32_32x32x16_bf16 v[18:33], v[70:73], v[154:157], v[18:33]
	s_waitcnt lgkmcnt(5)
	v_mfma_f32_32x32x16_bf16 v[34:49], v[74:77], v[154:157], v[34:49]
	s_waitcnt lgkmcnt(4)
	v_mfma_f32_32x32x16_bf16 v[50:65], v[78:81], v[154:157], v[50:65]
	s_waitcnt lgkmcnt(3)
	v_mfma_f32_32x32x16_bf16 v[2:17], v[82:85], v[158:161], v[2:17]
	s_waitcnt lgkmcnt(2)
	v_mfma_f32_32x32x16_bf16 v[18:33], v[86:89], v[158:161], v[18:33]
	s_waitcnt lgkmcnt(1)
	v_mfma_f32_32x32x16_bf16 v[34:49], v[90:93], v[158:161], v[34:49]
	s_waitcnt lgkmcnt(0)
	v_mfma_f32_32x32x16_bf16 v[50:65], v[94:97], v[158:161], v[50:65]
.Lat_x_nopv:
	s_cmp_gt_i32 s22, s25
	s_cbranch_scc1 .Lat_x_noqk
	ds_read_b128 v[146:149], v0 offset:128
	ds_read_b128 v[150:153], v0 offset:12928
	s_waitcnt lgkmcnt(8)
	v_mfma_f32_32x32x16_bf16 v[66:81], v[162:165], v[98:101], 0
	v_mfma_f32_32x32x16_bf16 v[82:97], v[166:169], v[98:101], 0
	ds_read_b128 v[154:157], v0 offset:160
	ds_read_b128 v[158:161], v0 offset:12960
	s_waitcnt lgkmcnt(8)
	v_mfma_f32_32x32x16_bf16 v[66:81], v[170:173], v[102:105], v[66:81]
	v_mfma_f32_32x32x16_bf16 v[82:97], v[174:177], v[102:105], v[82:97]
	ds_read_b128 v[162:165], v0 offset:192
	ds_read_b128 v[166:169], v0 offset:12992
	s_waitcnt lgkmcnt(8)
	v_mfma_f32_32x32x16_bf16 v[66:81], v[178:181], v[106:109], v[66:81]
	v_mfma_f32_32x32x16_bf16 v[82:97], v[182:185], v[106:109], v[82:97]
	ds_read_b128 v[170:173], v0 offset:224
	ds_read_b128 v[174:177], v0 offset:13024
	s_waitcnt lgkmcnt(8)
	v_mfma_f32_32x32x16_bf16 v[66:81], v[186:189], v[110:113], v[66:81]
	v_mfma_f32_32x32x16_bf16 v[82:97], v[190:193], v[110:113], v[82:97]
	ds_read_b128 v[178:181], v0 offset:256
	ds_read_b128 v[182:185], v0 offset:13056
	s_waitcnt lgkmcnt(8)
	v_mfma_f32_32x32x16_bf16 v[66:81], v[146:149], v[114:117], v[66:81]
	v_mfma_f32_32x32x16_bf16 v[82:97], v[150:153], v[114:117], v[82:97]
	ds_read_b128 v[186:189], v0 offset:288
	ds_read_b128 v[190:193], v0 offset:13088
	s_waitcnt lgkmcnt(8)
	v_mfma_f32_32x32x16_bf16 v[66:81], v[154:157], v[118:121], v[66:81]
	v_mfma_f32_32x32x16_bf16 v[82:97], v[158:161], v[118:121], v[82:97]
	ds_read_b128 v[146:149], v0 offset:320
	ds_read_b128 v[150:153], v0 offset:13120
	s_waitcnt lgkmcnt(8)
	v_mfma_f32_32x32x16_bf16 v[66:81], v[162:165], v[122:125], v[66:81]
	v_mfma_f32_32x32x16_bf16 v[82:97], v[166:169], v[122:125], v[82:97]
	ds_read_b128 v[154:157], v0 offset:352
	ds_read_b128 v[158:161], v0 offset:13152
	s_waitcnt lgkmcnt(8)
	v_mfma_f32_32x32x16_bf16 v[66:81], v[170:173], v[126:129], v[66:81]
	v_mfma_f32_32x32x16_bf16 v[82:97], v[174:177], v[126:129], v[82:97]
	s_waitcnt lgkmcnt(6)
	v_mfma_f32_32x32x16_bf16 v[66:81], v[178:181], v[130:133], v[66:81]
	v_mfma_f32_32x32x16_bf16 v[82:97], v[182:185], v[130:133], v[82:97]
	s_waitcnt lgkmcnt(4)
	v_mfma_f32_32x32x16_bf16 v[66:81], v[186:189], v[134:137], v[66:81]
	v_mfma_f32_32x32x16_bf16 v[82:97], v[190:193], v[134:137], v[82:97]
	s_waitcnt lgkmcnt(2)
	v_mfma_f32_32x32x16_bf16 v[66:81], v[146:149], v[138:141], v[66:81]
	v_mfma_f32_32x32x16_bf16 v[82:97], v[150:153], v[138:141], v[82:97]
	s_waitcnt lgkmcnt(0)
	v_mfma_f32_32x32x16_bf16 v[66:81], v[154:157], v[142:145], v[66:81]
	v_mfma_f32_32x32x16_bf16 v[82:97], v[158:161], v[142:145], v[82:97]
	s_lshl_b32 s39, s24, 8
	v_add_u32_e32 v0, s39, v232
	ds_read_b128 v[162:165], v0
	ds_read_b128 v[166:169], v0 offset:32
	ds_read_b128 v[170:173], v0 offset:64
	ds_read_b128 v[174:177], v0 offset:96
	ds_read_b128 v[178:181], v0 offset:128
	ds_read_b128 v[182:185], v0 offset:160
	ds_read_b128 v[186:189], v0 offset:192
	ds_read_b128 v[190:193], v0 offset:224

.Lat_ya:
	s_nop 7
	s_waitcnt lgkmcnt(0)
	v_mul_f32_e32 v66, v66, v162
	v_mul_f32_e32 v67, v67, v163
	v_mul_f32_e32 v68, v68, v164
	v_mul_f32_e32 v69, v69, v165
	v_mul_f32_e32 v70, v70, v166
	v_mul_f32_e32 v71, v71, v167
	v_mul_f32_e32 v72, v72, v168
	v_mul_f32_e32 v73, v73, v169
	v_mul_f32_e32 v74, v74, v170
	v_mul_f32_e32 v75, v75, v171
	v_mul_f32_e32 v76, v76, v172
	v_mul_f32_e32 v77, v77, v173
	v_mul_f32_e32 v78, v78, v174
	v_mul_f32_e32 v79, v79, v175
	v_mul_f32_e32 v80, v80, v176
	v_mul_f32_e32 v81, v81, v177
	v_mul_f32_e32 v82, v82, v178
	v_mul_f32_e32 v83, v83, v179
	v_mul_f32_e32 v84, v84, v180
	v_mul_f32_e32 v85, v85, v181
	v_mul_f32_e32 v86, v86, v182
	v_mul_f32_e32 v87, v87, v183
	v_mul_f32_e32 v88, v88, v184
	v_mul_f32_e32 v89, v89, v185
	v_mul_f32_e32 v90, v90, v186
	v_mul_f32_e32 v91, v91, v187
	v_mul_f32_e32 v92, v92, v188
	v_mul_f32_e32 v93, v93, v189
	v_mul_f32_e32 v94, v94, v190
	v_mul_f32_e32 v95, v95, v191
	v_mul_f32_e32 v96, v96, v192
	v_mul_f32_e32 v97, v97, v193
	s_lshl_b32 s65, s22, 6
	s_add_i32 s72, s65, 63
	s_cmp_le_i32 s72, s64
	s_cbranch_scc1 .Lat_y_nomask
	v_subrev_u32_e32 v242, s65, v239
	v_cmp_gt_i32_e32 vcc, 0, v242
	v_cmp_gt_i32_e64 s[36:37], 1, v242
	s_nop 0
	v_cndmask_b32_e32 v66, v66, v238, vcc
	v_cndmask_b32_e64 v67, v67, v238, s[36:37]
	v_cmp_gt_i32_e32 vcc, 2, v242
	v_cmp_gt_i32_e64 s[36:37], 3, v242
	s_nop 0
	v_cndmask_b32_e32 v68, v68, v238, vcc
	v_cndmask_b32_e64 v69, v69, v238, s[36:37]
	v_cmp_gt_i32_e32 vcc, 8, v242
	v_cmp_gt_i32_e64 s[36:37], 9, v242
	s_nop 0
	v_cndmask_b32_e32 v70, v70, v238, vcc
	v_cndmask_b32_e64 v71, v71, v238, s[36:37]
	v_cmp_gt_i32_e32 vcc, 10, v242
	v_cmp_gt_i32_e64 s[36:37], 11, v242
	s_nop 0
	v_cndmask_b32_e32 v72, v72, v238, vcc
	v_cndmask_b32_e64 v73, v73, v238, s[36:37]
	v_cmp_gt_i32_e32 vcc, 16, v242
	v_cmp_gt_i32_e64 s[36:37], 17, v242
	s_nop 0
	v_cndmask_b32_e32 v74, v74, v238, vcc
	v_cndmask_b32_e64 v75, v75, v238, s[36:37]
	v_cmp_gt_i32_e32 vcc, 18, v242
	v_cmp_gt_i32_e64 s[36:37], 19, v242
	s_nop 0
	v_cndmask_b32_e32 v76, v76, v238, vcc
	v_cndmask_b32_e64 v77, v77, v238, s[36:37]
	v_cmp_gt_i32_e32 vcc, 24, v242
	v_cmp_gt_i32_e64 s[36:37], 25, v242
	s_nop 0
	v_cndmask_b32_e32 v78, v78, v238, vcc
	v_cndmask_b32_e64 v79, v79, v238, s[36:37]
	v_cmp_gt_i32_e32 vcc, 26, v242
	v_cmp_gt_i32_e64 s[36:37], 27, v242
	s_nop 0
	v_cndmask_b32_e32 v80, v80, v238, vcc
	v_cndmask_b32_e64 v81, v81, v238, s[36:37]
	v_cmp_gt_i32_e32 vcc, 32, v242
	v_cmp_gt_i32_e64 s[36:37], 33, v242
	s_nop 0
	v_cndmask_b32_e32 v82, v82, v238, vcc
	v_cndmask_b32_e64 v83, v83, v238, s[36:37]
	v_cmp_gt_i32_e32 vcc, 34, v242
	v_cmp_gt_i32_e64 s[36:37], 35, v242
	s_nop 0
	v_cndmask_b32_e32 v84, v84, v238, vcc
	v_cndmask_b32_e64 v85, v85, v238, s[36:37]
	v_cmp_gt_i32_e32 vcc, 40, v242
	v_cmp_gt_i32_e64 s[36:37], 41, v242
	s_nop 0
	v_cndmask_b32_e32 v86, v86, v238, vcc
	v_cndmask_b32_e64 v87, v87, v238, s[36:37]
	v_cmp_gt_i32_e32 vcc, 42, v242
	v_cmp_gt_i32_e64 s[36:37], 43, v242
	s_nop 0
	v_cndmask_b32_e32 v88, v88, v238, vcc
	v_cndmask_b32_e64 v89, v89, v238, s[36:37]
	v_cmp_gt_i32_e32 vcc, 48, v242
	v_cmp_gt_i32_e64 s[36:37], 49, v242
	s_nop 0
	v_cndmask_b32_e32 v90, v90, v238, vcc
	v_cndmask_b32_e64 v91, v91, v238, s[36:37]
	v_cmp_gt_i32_e32 vcc, 50, v242
	v_cmp_gt_i32_e64 s[36:37], 51, v242
	s_nop 0
	v_cndmask_b32_e32 v92, v92, v238, vcc
	v_cndmask_b32_e64 v93, v93, v238, s[36:37]
	v_cmp_gt_i32_e32 vcc, 56, v242
	v_cmp_gt_i32_e64 s[36:37], 57, v242
	s_nop 0
	v_cndmask_b32_e32 v94, v94, v238, vcc
	v_cndmask_b32_e64 v95, v95, v238, s[36:37]
	v_cmp_gt_i32_e32 vcc, 58, v242
	v_cmp_gt_i32_e64 s[36:37], 59, v242
	s_nop 0
	v_cndmask_b32_e32 v96, v96, v238, vcc
	v_cndmask_b32_e64 v97, v97, v238, s[36:37]
.Lat_y_nomask:
	v_max3_f32 v247, v66, v67, v68
	v_max3_f32 v0, v82, v83, v84
	v_max3_f32 v247, v247, v69, v70
	v_max3_f32 v0, v0, v85, v86
	v_max3_f32 v247, v247, v71, v72
	v_max3_f32 v0, v0, v87, v88
	v_max3_f32 v247, v247, v73, v74
	v_max3_f32 v0, v0, v89, v90
	v_max3_f32 v247, v247, v75, v76
	v_max3_f32 v0, v0, v91, v92
	v_max3_f32 v247, v247, v77, v78
	v_max3_f32 v0, v0, v93, v94
	v_max3_f32 v247, v247, v79, v80
	v_max3_f32 v0, v0, v95, v96
	v_max3_f32 v247, v247, v81, v97
	v_max_f32_e32 v247, v247, v0
	v_mov_b32_e32 v0, v247
	s_nop 1
	v_permlane32_swap_b32_e32 v0, v247
	s_nop 1
	v_max_f32_e32 v247, v247, v0
	v_mul_f32_e32 v0, v235, v247
	v_sub_f32_e32 v194, v0, v236
	v_cmp_lt_f32_e32 vcc, 0x41000000, v194
	s_nop 1
	v_cndmask_b32_e32 v195, v236, v0, vcc
	v_sub_f32_e32 v248, v236, v195
	v_exp_f32_e32 v248, v248
	s_nop 0
	s_cbranch_vccz .Lat_y_norescale
	v_pk_mul_f32 v[2:3], v[2:3], v[248:249] op_sel_hi:[1,0]
	v_pk_mul_f32 v[4:5], v[4:5], v[248:249] op_sel_hi:[1,0]
	v_pk_mul_f32 v[6:7], v[6:7], v[248:249] op_sel_hi:[1,0]
	v_pk_mul_f32 v[8:9], v[8:9], v[248:249] op_sel_hi:[1,0]
	v_pk_mul_f32 v[10:11], v[10:11], v[248:249] op_sel_hi:[1,0]
	v_pk_mul_f32 v[12:13], v[12:13], v[248:249] op_sel_hi:[1,0]
	v_pk_mul_f32 v[14:15], v[14:15], v[248:249] op_sel_hi:[1,0]
	v_pk_mul_f32 v[16:17], v[16:17], v[248:249] op_sel_hi:[1,0]
	v_pk_mul_f32 v[18:19], v[18:19], v[248:249] op_sel_hi:[1,0]
	v_pk_mul_f32 v[20:21], v[20:21], v[248:249] op_sel_hi:[1,0]
	v_pk_mul_f32 v[22:23], v[22:23], v[248:249] op_sel_hi:[1,0]
	v_pk_mul_f32 v[24:25], v[24:25], v[248:249] op_sel_hi:[1,0]
	v_pk_mul_f32 v[26:27], v[26:27], v[248:249] op_sel_hi:[1,0]
	v_pk_mul_f32 v[28:29], v[28:29], v[248:249] op_sel_hi:[1,0]
	v_pk_mul_f32 v[30:31], v[30:31], v[248:249] op_sel_hi:[1,0]
	v_pk_mul_f32 v[32:33], v[32:33], v[248:249] op_sel_hi:[1,0]
	v_pk_mul_f32 v[34:35], v[34:35], v[248:249] op_sel_hi:[1,0]
	v_pk_mul_f32 v[36:37], v[36:37], v[248:249] op_sel_hi:[1,0]
	v_pk_mul_f32 v[38:39], v[38:39], v[248:249] op_sel_hi:[1,0]
	v_pk_mul_f32 v[40:41], v[40:41], v[248:249] op_sel_hi:[1,0]
	v_pk_mul_f32 v[42:43], v[42:43], v[248:249] op_sel_hi:[1,0]
	v_pk_mul_f32 v[44:45], v[44:45], v[248:249] op_sel_hi:[1,0]
	v_pk_mul_f32 v[46:47], v[46:47], v[248:249] op_sel_hi:[1,0]
	v_pk_mul_f32 v[48:49], v[48:49], v[248:249] op_sel_hi:[1,0]
	v_pk_mul_f32 v[50:51], v[50:51], v[248:249] op_sel_hi:[1,0]
	v_pk_mul_f32 v[52:53], v[52:53], v[248:249] op_sel_hi:[1,0]
	v_pk_mul_f32 v[54:55], v[54:55], v[248:249] op_sel_hi:[1,0]
	v_pk_mul_f32 v[56:57], v[56:57], v[248:249] op_sel_hi:[1,0]
	v_pk_mul_f32 v[58:59], v[58:59], v[248:249] op_sel_hi:[1,0]
	v_pk_mul_f32 v[60:61], v[60:61], v[248:249] op_sel_hi:[1,0]
	v_pk_mul_f32 v[62:63], v[62:63], v[248:249] op_sel_hi:[1,0]
	v_pk_mul_f32 v[64:65], v[64:65], v[248:249] op_sel_hi:[1,0]
.Lat_y_norescale:
	v_fma_f32 v66, v235, v66, -v195
	v_fma_f32 v67, v235, v67, -v195
	v_exp_f32_e32 v66, v66
	v_fma_f32 v68, v235, v68, -v195
	v_exp_f32_e32 v67, v67
	v_fma_f32 v69, v235, v69, -v195
	v_exp_f32_e32 v68, v68
	v_fma_f32 v70, v235, v70, -v195
	v_exp_f32_e32 v69, v69
	v_fma_f32 v71, v235, v71, -v195
	v_exp_f32_e32 v70, v70
	v_fma_f32 v72, v235, v72, -v195
	v_exp_f32_e32 v71, v71
	v_fma_f32 v73, v235, v73, -v195
	v_exp_f32_e32 v72, v72
	v_fma_f32 v74, v235, v74, -v195
	v_exp_f32_e32 v73, v73
	v_fma_f32 v75, v235, v75, -v195
	v_exp_f32_e32 v74, v74
	v_fma_f32 v76, v235, v76, -v195
	v_exp_f32_e32 v75, v75
	v_fma_f32 v77, v235, v77, -v195
	v_exp_f32_e32 v76, v76
	v_fma_f32 v78, v235, v78, -v195
	v_exp_f32_e32 v77, v77
	v_fma_f32 v79, v235, v79, -v195
	v_exp_f32_e32 v78, v78
	v_fma_f32 v80, v235, v80, -v195
	v_exp_f32_e32 v79, v79
	v_fma_f32 v81, v235, v81, -v195
	v_exp_f32_e32 v80, v80
	v_fma_f32 v82, v235, v82, -v195
	v_exp_f32_e32 v81, v81
	v_fma_f32 v83, v235, v83, -v195
	v_exp_f32_e32 v82, v82
	v_fma_f32 v84, v235, v84, -v195
	v_exp_f32_e32 v83, v83
	v_fma_f32 v85, v235, v85, -v195
	v_exp_f32_e32 v84, v84
	v_fma_f32 v86, v235, v86, -v195
	v_exp_f32_e32 v85, v85
	v_fma_f32 v87, v235, v87, -v195
	v_exp_f32_e32 v86, v86
	v_fma_f32 v88, v235, v88, -v195
	v_exp_f32_e32 v87, v87
	v_fma_f32 v89, v235, v89, -v195
	v_exp_f32_e32 v88, v88
	v_fma_f32 v90, v235, v90, -v195
	v_exp_f32_e32 v89, v89
	v_fma_f32 v91, v235, v91, -v195
	v_exp_f32_e32 v90, v90
	v_fma_f32 v92, v235, v92, -v195
	v_exp_f32_e32 v91, v91
	v_fma_f32 v93, v235, v93, -v195
	v_exp_f32_e32 v92, v92
	v_fma_f32 v94, v235, v94, -v195
	v_exp_f32_e32 v93, v93
	v_fma_f32 v95, v235, v95, -v195
	v_exp_f32_e32 v94, v94
	v_fma_f32 v96, v235, v96, -v195
	v_exp_f32_e32 v95, v95
	v_fma_f32 v97, v235, v97, -v195
	v_exp_f32_e32 v96, v96
	v_exp_f32_e32 v97, v97
	s_nop 0
	v_add_f32_e32 v162, v66, v70
	v_add_f32_e32 v163, v67, v71
	v_add_f32_e32 v164, v68, v72
	v_add_f32_e32 v165, v69, v73
	v_add_f32_e32 v162, v162, v74
	v_add_f32_e32 v163, v163, v75
	v_add_f32_e32 v164, v164, v76
	v_add_f32_e32 v165, v165, v77
	v_add_f32_e32 v162, v162, v78
	v_add_f32_e32 v163, v163, v79
	v_add_f32_e32 v164, v164, v80
	v_add_f32_e32 v165, v165, v81
	v_add_f32_e32 v162, v162, v82
	v_add_f32_e32 v163, v163, v83
	v_add_f32_e32 v164, v164, v84
	v_add_f32_e32 v165, v165, v85
	v_add_f32_e32 v162, v162, v86
	v_add_f32_e32 v163, v163, v87
	v_add_f32_e32 v164, v164, v88
	v_add_f32_e32 v165, v165, v89
	v_add_f32_e32 v162, v162, v90
	v_add_f32_e32 v163, v163, v91
	v_add_f32_e32 v164, v164, v92
	v_add_f32_e32 v165, v165, v93
	v_add_f32_e32 v162, v162, v94
	v_add_f32_e32 v163, v163, v95
	v_add_f32_e32 v164, v164, v96
	v_add_f32_e32 v165, v165, v97
	v_add_f32_e32 v162, v162, v163
	v_add_f32_e32 v164, v164, v165
	v_add_f32_e32 v163, v162, v164
	v_mov_b32_e32 v236, v195
	v_fma_f32 v237, v237, v248, v163
	v_cvt_pk_bf16_f32 v146, v66, v67
	v_cvt_pk_bf16_f32 v147, v68, v69
	v_cvt_pk_bf16_f32 v148, v70, v71
	v_cvt_pk_bf16_f32 v149, v72, v73
	v_cvt_pk_bf16_f32 v150, v74, v75
	v_cvt_pk_bf16_f32 v151, v76, v77
	v_cvt_pk_bf16_f32 v152, v78, v79
	v_cvt_pk_bf16_f32 v153, v80, v81
	v_cvt_pk_bf16_f32 v154, v82, v83
	v_cvt_pk_bf16_f32 v155, v84, v85
	v_cvt_pk_bf16_f32 v156, v86, v87
	v_cvt_pk_bf16_f32 v157, v88, v89
	v_cvt_pk_bf16_f32 v158, v90, v91
	v_cvt_pk_bf16_f32 v159, v92, v93
	v_cvt_pk_bf16_f32 v160, v94, v95
	v_cvt_pk_bf16_f32 v161, v96, v97
	s_branch .Lat_y_done

.Lat_yz:
	s_add_i32 s22, s22, 1
	s_add_i32 s24, s24, 1
	s_cmp_eq_u32 s24, 3
	s_cselect_b32 s24, 0, s24
	s_cmp_lt_u32 s22, s23
	s_cbranch_scc1 .Lat_loop
	s_add_i32 s65, s23, -1
	s_cmp_gt_i32 s65, s25
	s_cbranch_scc1 .Lat_f_nopv
	s_add_i32 s72, s24, 2
	s_cmp_ge_u32 s72, 3
	s_cbranch_scc0 .Lat_f_pvb
	s_sub_i32 s72, s72, 3
